# B1 prep: L2 prefetch of the next prep item's first cache lines (one 4-byte load per lane) while the current item computes
# baseline (speedup 1.0000x reference)
.Lpc_join:
	s_mov_b64 s[22:23], exec
	s_and_b64 exec, exec, s[38:39]
	v_mov_b32_e32 v29, 0x2400c
	ds_write_b32 v29, v205
	s_mov_b64 exec, s[22:23]
	v_lshlrev_b32_e32 v16, 16, v16
	v_lshlrev_b32_e32 v17, 16, v17
	v_lshlrev_b32_e32 v18, 16, v18
	v_lshlrev_b32_e32 v19, 16, v19
	v_sub_f32_e32 v24, v24, v16
	v_sub_f32_e32 v25, v25, v17
	v_sub_f32_e32 v26, v26, v18
	v_sub_f32_e32 v27, v27, v19
	v_fmac_f32_e32 v16, v3, v24
	v_fmac_f32_e32 v17, v3, v25
	v_fmac_f32_e32 v18, v3, v26
	v_fmac_f32_e32 v19, v3, v27
	v_mul_u32_u24_e32 v28, 0x90, v6
	v_add_u32_e32 v28, v28, v4
	s_cmpk_ge_u32 s0, 0x180
	s_cbranch_scc1 .Lpc_nostage2
	v_lshlrev_b32_e32 v29, 3, v130
	ds_write_b64 v29, v[30:31] offset:4608

.Lpc_done:
	v_mul_u32_u24_e32 v2, 0x48, v98
	v_lshlrev_b32_e32 v2, 1, v2
	v_lshlrev_b32_e32 v3, 4, v207
	v_add3_u32 v2, 0, v2, v3
	s_waitcnt lgkmcnt(0)
	s_barrier
	ds_read_b128 v[32:35], v2
	ds_read_b128 v[24:27], v2 offset:64
	ds_read_b128 v[28:31], v2 offset:2304
	ds_read_b128 v[20:23], v2 offset:2368
	v_ashrrev_i32_e32 v148, 6, v130
	s_movk_i32 s0, 0x3fff
	v_ashrrev_i32_e32 v135, 31, v134
	v_cmp_lt_i32_e32 vcc, s0, v134
	v_ashrrev_i32_e32 v149, 31, v148
	s_and_saveexec_b64 s[0:1], vcc
	s_xor_b64 s[0:1], exec, s[0:1]
	v_lshl_add_u64 v[78:79], v[134:135], 3, v[148:149]
	s_andn2_saveexec_b64 s[0:1], s[0:1]
	v_ashrrev_i32_e32 v2, 8, v132
	v_and_b32_e32 v2, -8, v2
	v_add_u32_e32 v2, v148, v2
	v_ashrrev_i32_e32 v3, 31, v2
	v_lshlrev_b64 v[78:79], 11, v[2:3]
	s_movk_i32 s2, 0x7ff
	v_and_or_b32 v78, v134, s2, v78
	s_or_b64 exec, exec, s[0:1]
	v_mov_b32_e32 v4, 0x2400c
	ds_read_b32 v5, v4
	v_mul_u32_u24_e32 v6, 0x9d9, v130
	v_lshrrev_b32_e32 v6, 16, v6
	v_mul_u32_u24_e32 v7, 26, v6
	v_sub_u32_e32 v7, v130, v7
	s_waitcnt lgkmcnt(0)
	v_readfirstlane_b32 s0, v5
	s_nop 0
	s_cmpk_lt_u32 s0, 0x408
	s_cbranch_scc0 .Lpc_nopf
	s_lshl_b32 s0, s0, 4
	s_sub_i32 s0, s0, 1
	s_max_i32 s0, s0, 0
	v_add_u32_e32 v6, s0, v6
	v_min_u32_e32 v6, 0x407f, v6
	v_mul_lo_u32 v6, v6, s83
	v_lshl_add_u32 v6, v7, 7, v6
	global_load_dword a16, v6, s[20:21] offset:1024
.Lpc_nopf:
	v_lshlrev_b32_e32 v6, 1, v0
	v_mov_b32_e32 v7, v65
	v_lshl_add_u64 v[160:161], v[126:127], 0, v[6:7]
	v_lshlrev_b32_e32 v8, 7, v98
	v_mov_b32_e32 v9, v65
	v_lshl_add_u64 v[74:75], v[160:161], 0, v[8:9]
	ds_read_b128 v[2:5], v217 offset:0
	v_lshl_add_u64 v[162:163], v[128:129], 0, v[6:7]
	v_lshl_add_u64 v[76:77], v[162:163], 0, v[8:9]
	ds_read_b128 v[6:9], v217 offset:1024
	ds_read_b128 v[12:15], v217 offset:2048
	ds_read_b128 v[16:19], v217 offset:3072
	v_lshlrev_b32_e32 v64, 2, v207
	v_or_b32_e32 v10, v98, v1
	v_add_u32_e32 v11, 0xffffc000, v134
	v_mov_b64_e32 v[0:1], s[64:65]
	v_lshl_add_u32 v208, v64, 2, v204
	v_cmp_ne_u32_e64 s[0:1], 0, v10
	v_mad_i64_i32 v[158:159], s[20:21], v11, s86, v[0:1]
	v_or_b32_e32 v80, v64, v150
	s_waitcnt lgkmcnt(0)
	v_mfma_f32_16x16x32_bf16 v[52:55], v[6:9], v[28:31], 0
	v_mfma_f32_16x16x32_bf16 v[36:39], v[2:5], v[32:35], 0
	ds_read_b128 v[0:3], v208 offset:8192
	ds_read_b128 v[48:51], v208 offset:8448
	ds_read_b128 v[8:11], v208 offset:8704
	ds_read_b128 v[40:43], v208 offset:8960
	s_nop 0
	v_mfma_f32_16x16x32_bf16 v[66:69], v[12:15], v[24:27], v[36:39]
	ds_read_b128 v[4:7], v208 offset:9216
	ds_read_b128 v[12:15], v208 offset:9472
	ds_read_b128 v[44:47], v208 offset:9728
	ds_read_b128 v[36:39], v208 offset:9984
	s_waitcnt lgkmcnt(8)
	v_mfma_f32_16x16x32_bf16 v[52:55], v[16:19], v[20:23], v[52:55]
	s_and_saveexec_b64 s[20:21], s[40:41]
	s_xor_b64 s[20:21], exec, s[20:21]
	s_cbranch_execz .LBB0_452
	v_ashrrev_i32_e32 v81, 31, v80
	v_lshl_add_u64 v[60:61], v[80:81], 2, v[158:159]
	global_load_dwordx4 v[16:19], v[60:61], off
	global_load_dwordx4 v[56:59], v[60:61], off offset:2048
	v_add_co_u32_e32 v60, vcc, 0x1000, v60
	s_nop 1
	v_addc_co_u32_e32 v61, vcc, 0, v61, vcc
	global_load_dwordx4 v[60:63], v[60:61], off
